# v17 + P2..P4 use XCD-contiguous unit ids (id = (bx&7)*32 + bx>>3): units sharing a head land on one XCD, parity split is within-XCD
# speedup vs baseline: 1.0237x; 1.0058x over previous
; #define LAS __attribute__((address_space(3)))
; DI float bf2f(unsigned short u) { return __uint_as_float(((unsigned)u) << 16); }
; DI float gamma_of(int h) { return 1.0f - exp2f(-5.0f - (float)h); }
; DI void ret_decode_unit(LAS unsigned char* lds, const bf16_t* Z, const float* S0, float* S1, bf16_t* MIX, const float* rng, int b, int h, int tid) {
;     LAS float* qv = (LAS float*)lds; LAS float* red = qv + 768;
;     const int lane = tid & 63, wid = tid >> 6;
;     const bf16_t* zrow = Z + (size_t)(LP + b) * INW;
;     if (tid < 256) { qv[tid] = bf2f(zrow[C_RQ + h * 256 + tid]); qv[256 + tid] = bf2f(zrow[C_RK + h * 256 + tid]); qv[512 + tid] = bf2f(zrow[C_RV + h * 256 + tid]); }
;     __syncthreads();
;     const float gm = gamma_of(h);
;     const f32x4 v4 = *(const LAS f32x4*)(qv + 512 + 4 * lane);
;     f32x4 acc = {0.f, 0.f, 0.f, 0.f};
;     const size_t off = ((size_t)(b * 4 + h) * 256 + wid * 32) * 256 + 4 * lane;
;     const float* s0 = S0 + off; float* s1 = S1 + off;
; __global__ void __launch_bounds__(512, 2) fwd_kernel(Args a) {
;     ...
;     if (IN(2)) for (int rep_ = 0; rep_ < 1 + ((DUPMASK >> 2) & 1); ++rep_) { if (rep_) xcd_barrier(bar);
;         if (bx & 1) for (int u = bx; u < 256; u += G) ret_decode_unit(lds, Z, state0, out + O_SS, MIX, rng, u >> 2, u & 3, tid);
;         for (int u = bx; u < 256; u += G) ret_step1(lds, Z, KV, u >> 2, u & 3, tid);
;         if (!(bx & 1)) for (int u = bx; u < 256; u += G) ret_decode_unit(lds, Z, state0, out + O_SS, MIX, rng, u >> 2, u & 3, tid);
;     }
.LBB0_226:
	s_and_b32 s98, s92, 7
	s_lshl_b32 s98, s98, 5
	s_lshr_b32 s99, s92, 3
	s_or_b32 s92, s98, s99
	s_cmp_lt_i32 s62, 3
	s_cselect_b64 s[2:3], -1, 0
	s_add_u32 s56, s60, 0x8000000
	s_addc_u32 s57, s61, 0
	s_add_u32 s4, s60, 0xfc00000
	s_addc_u32 s5, s61, 0
	v_writelane_b32 v254, s4, 23
	s_and_b64 s[10:11], s[2:3], s[0:1]
	s_andn2_b64 vcc, exec, s[10:11]
	v_writelane_b32 v254, s5, 24
	v_lshrrev_b32_e32 v252, 6, v253
	v_cmp_gt_u32_e64 s[0:1], 64, v253
	s_cbranch_vccnz .LBB0_250
	s_bitcmp0_b32 s92, 0
	v_readlane_b32 s68, v254, 7
	s_cselect_b64 s[14:15], -1, 0
	s_cmpk_gt_i32 s92, 0xff
	v_readlane_b32 s82, v254, 21
	v_lshlrev_b32_e32 v0, 2, v253
	s_cselect_b64 s[2:3], -1, 0
	v_readlane_b32 s83, v254, 22
	s_add_u32 s12, s82, 0x5220000
	v_and_b32_e32 v147, 0xfc, v0
	v_readlane_b32 s72, v254, 11
	v_readlane_b32 s73, v254, 12
	s_addc_u32 s13, s83, 0
	s_movk_i32 s4, 0x100
	v_add_u32_e32 v146, 0, v0
	v_lshlrev_b32_e32 v20, 2, v147
	v_mov_b32_e32 v21, 0
	v_lshl_add_u32 v149, v252, 7, 0
	v_mul_u32_u24_e32 v0, 0x380, v252
	s_or_b64 s[2:3], s[14:15], s[2:3]
	s_mov_b32 s17, 0
	v_add_u32_e32 v144, 0x900, v253
	v_add_u32_e32 v145, 0xd00, v253
	v_cmp_gt_u32_e64 s[6:7], s4, v253
	v_add_u32_e32 v148, 0, v20
	v_lshl_or_b32 v128, v252, 13, v147
	v_mov_b32_e32 v129, v21
	v_add3_u32 v150, v149, v0, v20
	v_lshl_add_u64 v[130:131], s[72:73], 0, v[20:21]
	s_and_b64 vcc, exec, s[2:3]
	v_readlane_b32 s69, v254, 8
	v_readlane_b32 s70, v254, 9
	v_readlane_b32 s71, v254, 10
	v_readlane_b32 s74, v254, 13
	v_readlane_b32 s75, v254, 14
	v_readlane_b32 s76, v254, 15
	v_readlane_b32 s77, v254, 16
	v_readlane_b32 s78, v254, 17
	v_readlane_b32 s79, v254, 18
	v_readlane_b32 s80, v254, 19
	v_readlane_b32 s81, v254, 20
	s_cbranch_vccnz .LBB0_236
	v_mbcnt_lo_u32_b32 v0, -1, 0
	v_mov_b32_e32 v30, 0x42800000
	v_mov_b32_e32 v31, 0x358637bd
	v_mbcnt_hi_u32_b32 v32, -1, v0
	s_mov_b32 s18, s92
	s_branch .LBB0_230

;     __host__ __device__ bool next(int i, Unit& u) const {
;         const long L = (long)i * G + c; if (L >= nwg) return false;
;         int wgid = (int)L; { const int q = nwg / NXCD, r = nwg % NXCD, xcd = wgid % NXCD, off = wgid / NXCD; wgid = (xcd < r ? xcd * (q + 1) : r * (q + 1) + (xcd - r) * q) + off; }
;         const int nig = wgm * nN, gid = wgid / nig, fm = gid * wgm, gsz = (nM - fm) < wgm ? (nM - fm) : wgm;
;         u.pm = fm + ((wgid % nig) % gsz); u.pn = (wgid % nig) / gsz; return true;
; __global__ void __launch_bounds__(512, 2) fwd_kernel(Args a) {
;     ...
;     if (IN(5)) for (int rep_ = 0; rep_ < 1 + ((DUPMASK >> 5) & 1); ++rep_) { if (rep_) xcd_barrier(bar);
;         pg8::Gemm g{MIX, WOUT, LP, DM, DM}; pg8::StaticOrder S; S.init(LP, DM, G, bx, WGM_OUT);
;         pg8::EpiOut E{x_p, XG, PART};
;         pg8::gemm_phase<pg8::EpiOut, pg8::StaticOrder, true, true>(lds, g, S, E);
.LBB0_511:
	s_and_b32 s98, s92, 31
	s_lshl_b32 s98, s98, 3
	s_lshr_b32 s99, s92, 5
	s_or_b32 s92, s98, s99
	s_cmp_lt_i32 s62, 6
	s_cselect_b64 s[2:3], -1, 0
	s_and_b64 s[6:7], s[2:3], s[0:1]
	s_andn2_b64 vcc, exec, s[6:7]
	s_cbranch_vccnz .LBB0_553
	s_cmpk_lt_i32 s92, 0x100
	s_cselect_b64 s[0:1], -1, 0
	s_cmpk_gt_i32 s92, 0xff
	v_readfirstlane_b32 s4, v253
	s_cbranch_scc1 .LBB0_514
	s_ashr_i32 s2, s92, 31
	s_lshr_b32 s2, s2, 29
	s_add_i32 s2, s92, s2
	s_and_b32 s3, s2, -8
	s_sub_i32 s3, s92, s3
	s_lshl_b32 s8, s3, 5
	s_ashr_i32 s2, s2, 3
	s_mul_i32 s5, s3, 33
	s_cmp_lt_i32 s3, 0
	s_cselect_b32 s3, s5, s8
	s_add_i32 s2, s3, s2
	s_ashr_i32 s3, s2, 31
	s_lshr_b32 s3, s3, 28
	s_add_i32 s3, s2, s3
	s_ashr_i32 s5, s3, 4
	s_and_b32 s3, s3, -16
	s_sub_i32 s2, s2, s3
	s_bfe_u32 s3, s2, 0x10007
	s_add_i32 s3, s2, s3
	s_bfe_i32 s8, s3, 0x80000
	s_and_b32 s3, s3, 0xfe
	s_sub_i32 s2, s2, s3
	s_lshl_b32 s5, s5, 1
	s_sext_i32_i16 s8, s8
	s_sext_i32_i8 s2, s2
	s_add_i32 s26, s5, s2
	s_ashr_i32 s8, s8, 1
